# grid barrier: L1 invalidate issued right after the arrival atomic returns (before the XCD-last's write-back) so it never trails the release
# speedup vs baseline: 1.0016x; 1.0016x over previous
; __device__ __forceinline__ unsigned xb_ld(unsigned* p)              { return __hip_atomic_load(p, __ATOMIC_RELAXED, __HIP_MEMORY_SCOPE_AGENT); }
; __device__ __forceinline__ unsigned xb_add(unsigned* p, unsigned v) { return __hip_atomic_fetch_add(p, v, __ATOMIC_RELAXED, __HIP_MEMORY_SCOPE_AGENT); }
; #define XB_SPIN(cond, bar) do { unsigned _sp = 0; while (cond) { __builtin_amdgcn_s_sleep(1); \
;     if ((++_sp & 255u) == 0u) { if (xb_ld(&(bar)[XB_TMO])) break; if (_sp > XB_SPIN_CAP) { atomicAdd(&(bar)[XB_TMO], 1u); break; } } } } while (0)
; __device__ __forceinline__ void xcd_barrier(const XcdBarrier& b) {
;     ...
;         __builtin_amdgcn_s_waitcnt(0);
;         unsigned nloc = b.st[0], nx = b.st[1];
;         if (nloc == 0u) { xcd_barrier_complete(bar, b.x, nloc, nx); b.st[0] = nloc; b.st[1] = nx; }
;         const unsigned old = xb_add(&bar[XB_XSUB(b.x)], 1u);
;         const unsigned gen = old / nloc;
;         if (old + 1u == (gen + 1u) * nloc) {
;             __builtin_amdgcn_fence(__ATOMIC_RELEASE, "agent");
;             asm volatile("s_waitcnt vmcnt(0)" ::: "memory");
;             const unsigned og = xb_add(&bar[XB_TOP], 1u);
;             const unsigned tg = og / nx;
;             __builtin_amdgcn_fence(__ATOMIC_ACQUIRE, "agent");
;             if (og + 1u == (tg + 1u) * nx) xb_add(&bar[XB_TOPGEN], 1u);
;             else XB_SPIN(xb_ld(&bar[XB_TOPGEN]) == tg, bar);
;             xb_add(&bar[XB_XGEN(b.x)], 1u);
;             asm volatile("s_waitcnt vmcnt(0)" ::: "memory");
;         } else {
;             __builtin_amdgcn_fence(__ATOMIC_ACQUIRE, "agent");
;             XB_SPIN(xb_ld(&bar[XB_XGEN(b.x)]) == gen, bar);
;             asm volatile("s_waitcnt vmcnt(0)" ::: "memory");
;         }
.LBB0_388:
	s_waitcnt vmcnt(0)
	s_waitcnt vmcnt(0) lgkmcnt(0)
	s_barrier
	s_mov_b64 s[10:11], exec
	v_readlane_b32 s8, v253, 41
	v_readlane_b32 s9, v253, 42
	s_and_b64 s[8:9], s[10:11], s[8:9]
	s_mov_b64 exec, s[8:9]
	s_cbranch_execz .LBB0_440
	s_waitcnt vmcnt(0) lgkmcnt(0)
	v_readlane_b32 s22, v255, 54
	v_readlane_b32 s24, v254, 51
	v_readlane_b32 s8, v254, 25
	v_readlane_b32 s9, v254, 26
	v_readlane_b32 s20, v254, 27
	v_readlane_b32 s21, v254, 28
	s_add_u32 s22, s22, 1
	v_mov_b32_e32 v0, s24
	ds_read_b32 v2, v0
	s_add_u32 s8, s8, 0x2c00
	s_addc_u32 s9, s9, 0
	s_add_u32 s20, s20, 0x2c00
	s_addc_u32 s21, s21, 0
	v_writelane_b32 v255, s22, 54
	v_mov_b32_e32 v1, 1
	v_mov_b32_e32 v3, 0
	s_nop 1
	global_atomic_add v4, v3, v1, s[8:9] sc0
	s_waitcnt vmcnt(0) lgkmcnt(0)
	v_readfirstlane_b32 s24, v4
	v_readfirstlane_b32 s23, v2
	buffer_inv sc1
	s_add_u32 s24, s24, 1
	s_mul_i32 s25, s23, s22
	s_cmp_lg_u32 s24, s25
	s_cbranch_scc1 .Lgd_notlast_0
	buffer_wbl2 sc1
	s_waitcnt vmcnt(0)
	v_readlane_b32 s8, v254, 29
	v_readlane_b32 s9, v254, 30
	v_mov_b32_e32 v5, s23
	s_add_u32 s8, s8, 0x1c00
	s_addc_u32 s9, s9, 0
	s_nop 4
	global_atomic_add v3, v5, s[8:9]
	global_atomic_add v3, v5, s[8:9] offset:256
	global_atomic_add v3, v5, s[8:9] offset:512
	global_atomic_add v3, v5, s[8:9] offset:768
	global_atomic_add v3, v5, s[8:9] offset:1024
	global_atomic_add v3, v5, s[8:9] offset:1280
	global_atomic_add v3, v5, s[8:9] offset:1536
	global_atomic_add v3, v5, s[8:9] offset:1792
	global_atomic_add v3, v5, s[8:9] offset:2048
	global_atomic_add v3, v5, s[8:9] offset:2304
	global_atomic_add v3, v5, s[8:9] offset:2560
	global_atomic_add v3, v5, s[8:9] offset:2816
	global_atomic_add v3, v5, s[8:9] offset:3072
	global_atomic_add v3, v5, s[8:9] offset:3328
	global_atomic_add v3, v5, s[8:9] offset:3584
	global_atomic_add v3, v5, s[8:9] offset:3840
.Lgd_notlast_0:
	s_lshl_b32 s22, s22, 8
	s_mov_b32 s25, 0

; __device__ __forceinline__ unsigned xb_ld(unsigned* p)              { return __hip_atomic_load(p, __ATOMIC_RELAXED, __HIP_MEMORY_SCOPE_AGENT); }
; __device__ __forceinline__ unsigned xb_add(unsigned* p, unsigned v) { return __hip_atomic_fetch_add(p, v, __ATOMIC_RELAXED, __HIP_MEMORY_SCOPE_AGENT); }
; #define XB_SPIN(cond, bar) do { unsigned _sp = 0; while (cond) { __builtin_amdgcn_s_sleep(1); \
;     if ((++_sp & 255u) == 0u) { if (xb_ld(&(bar)[XB_TMO])) break; if (_sp > XB_SPIN_CAP) { atomicAdd(&(bar)[XB_TMO], 1u); break; } } } } while (0)
; __device__ __forceinline__ void xcd_barrier(const XcdBarrier& b) {
;     ...
;         __builtin_amdgcn_s_waitcnt(0);
;         unsigned nloc = b.st[0], nx = b.st[1];
;         if (nloc == 0u) { xcd_barrier_complete(bar, b.x, nloc, nx); b.st[0] = nloc; b.st[1] = nx; }
;         const unsigned old = xb_add(&bar[XB_XSUB(b.x)], 1u);
;         const unsigned gen = old / nloc;
;         if (old + 1u == (gen + 1u) * nloc) {
;             __builtin_amdgcn_fence(__ATOMIC_RELEASE, "agent");
;             asm volatile("s_waitcnt vmcnt(0)" ::: "memory");
;             const unsigned og = xb_add(&bar[XB_TOP], 1u);
;             const unsigned tg = og / nx;
;             __builtin_amdgcn_fence(__ATOMIC_ACQUIRE, "agent");
;             if (og + 1u == (tg + 1u) * nx) xb_add(&bar[XB_TOPGEN], 1u);
;             else XB_SPIN(xb_ld(&bar[XB_TOPGEN]) == tg, bar);
;             xb_add(&bar[XB_XGEN(b.x)], 1u);
.LBB0_554:
	s_waitcnt vmcnt(0)
	s_waitcnt vmcnt(0)
	s_barrier
	s_mov_b64 s[10:11], exec
	v_readlane_b32 s8, v253, 41
	v_readlane_b32 s9, v253, 42
	v_readlane_b32 s64, v255, 3
	v_readlane_b32 s66, v255, 5
	v_readlane_b32 s68, v255, 7
	v_readlane_b32 s70, v255, 9
	v_readlane_b32 s72, v255, 11
	v_readlane_b32 s74, v255, 13
	v_readlane_b32 s76, v255, 15
	v_readlane_b32 s78, v255, 17
	v_readlane_b32 s84, v255, 19
	v_readlane_b32 s12, v255, 28
	s_and_b64 s[8:9], s[10:11], s[8:9]
	v_readlane_b32 s65, v255, 4
	v_readlane_b32 s67, v255, 6
	v_readlane_b32 s69, v255, 8
	v_readlane_b32 s71, v255, 10
	v_readlane_b32 s73, v255, 12
	v_readlane_b32 s75, v255, 14
	v_readlane_b32 s77, v255, 16
	v_readlane_b32 s79, v255, 18
	v_readlane_b32 s85, v255, 20
	v_readlane_b32 s14, v255, 30
	v_readlane_b32 s13, v255, 29
	v_readlane_b32 s15, v255, 31
	s_mov_b64 exec, s[8:9]
	s_cbranch_execz .LBB0_606
	s_waitcnt vmcnt(0) lgkmcnt(0)
	v_readlane_b32 s22, v255, 54
	v_readlane_b32 s24, v254, 51
	v_readlane_b32 s8, v254, 25
	v_readlane_b32 s9, v254, 26
	v_readlane_b32 s20, v254, 27
	v_readlane_b32 s21, v254, 28
	s_add_u32 s22, s22, 1
	v_mov_b32_e32 v0, s24
	ds_read_b32 v2, v0
	s_add_u32 s8, s8, 0x2c00
	s_addc_u32 s9, s9, 0
	s_add_u32 s20, s20, 0x2c00
	s_addc_u32 s21, s21, 0
	v_writelane_b32 v255, s22, 54
	v_mov_b32_e32 v1, 1
	v_mov_b32_e32 v3, 0
	s_nop 1
	global_atomic_add v4, v3, v1, s[8:9] sc0
	s_waitcnt vmcnt(0) lgkmcnt(0)
	v_readfirstlane_b32 s24, v4
	v_readfirstlane_b32 s23, v2
	buffer_inv sc1
	s_add_u32 s24, s24, 1
	s_mul_i32 s25, s23, s22
	s_cmp_lg_u32 s24, s25
	s_cbranch_scc1 .Lgd_notlast_1
	buffer_wbl2 sc1
	s_waitcnt vmcnt(0)
	v_readlane_b32 s8, v254, 29
	v_readlane_b32 s9, v254, 30
	v_mov_b32_e32 v5, s23
	s_add_u32 s8, s8, 0x1c00
	s_addc_u32 s9, s9, 0
	s_nop 4
	global_atomic_add v3, v5, s[8:9]
	global_atomic_add v3, v5, s[8:9] offset:256
	global_atomic_add v3, v5, s[8:9] offset:512
	global_atomic_add v3, v5, s[8:9] offset:768
	global_atomic_add v3, v5, s[8:9] offset:1024
	global_atomic_add v3, v5, s[8:9] offset:1280
	global_atomic_add v3, v5, s[8:9] offset:1536
	global_atomic_add v3, v5, s[8:9] offset:1792
	global_atomic_add v3, v5, s[8:9] offset:2048
	global_atomic_add v3, v5, s[8:9] offset:2304
	global_atomic_add v3, v5, s[8:9] offset:2560
	global_atomic_add v3, v5, s[8:9] offset:2816
	global_atomic_add v3, v5, s[8:9] offset:3072
	global_atomic_add v3, v5, s[8:9] offset:3328
	global_atomic_add v3, v5, s[8:9] offset:3584
	global_atomic_add v3, v5, s[8:9] offset:3840

; __device__ __forceinline__ unsigned xb_ld(unsigned* p)              { return __hip_atomic_load(p, __ATOMIC_RELAXED, __HIP_MEMORY_SCOPE_AGENT); }
; __device__ __forceinline__ unsigned xb_add(unsigned* p, unsigned v) { return __hip_atomic_fetch_add(p, v, __ATOMIC_RELAXED, __HIP_MEMORY_SCOPE_AGENT); }
; #define XB_SPIN(cond, bar) do { unsigned _sp = 0; while (cond) { __builtin_amdgcn_s_sleep(1); \
;     if ((++_sp & 255u) == 0u) { if (xb_ld(&(bar)[XB_TMO])) break; if (_sp > XB_SPIN_CAP) { atomicAdd(&(bar)[XB_TMO], 1u); break; } } } } while (0)
; __device__ __forceinline__ void xcd_barrier(const XcdBarrier& b) {
;     ...
;         __builtin_amdgcn_s_waitcnt(0);
;         unsigned nloc = b.st[0], nx = b.st[1];
;         if (nloc == 0u) { xcd_barrier_complete(bar, b.x, nloc, nx); b.st[0] = nloc; b.st[1] = nx; }
;         const unsigned old = xb_add(&bar[XB_XSUB(b.x)], 1u);
;         const unsigned gen = old / nloc;
;         if (old + 1u == (gen + 1u) * nloc) {
;             __builtin_amdgcn_fence(__ATOMIC_RELEASE, "agent");
;             asm volatile("s_waitcnt vmcnt(0)" ::: "memory");
;             const unsigned og = xb_add(&bar[XB_TOP], 1u);
;             const unsigned tg = og / nx;
;             __builtin_amdgcn_fence(__ATOMIC_ACQUIRE, "agent");
;             if (og + 1u == (tg + 1u) * nx) xb_add(&bar[XB_TOPGEN], 1u);
;             else XB_SPIN(xb_ld(&bar[XB_TOPGEN]) == tg, bar);
;             xb_add(&bar[XB_XGEN(b.x)], 1u);
.LBB0_789:
	s_waitcnt vmcnt(0)
	v_readlane_b32 s0, v253, 41
	v_readlane_b32 s1, v253, 42
	s_waitcnt lgkmcnt(0)
	s_barrier
	s_and_saveexec_b64 s[4:5], s[0:1]
	s_cbranch_execz .LBB0_841
	s_waitcnt vmcnt(0) lgkmcnt(0)
	v_readlane_b32 s22, v255, 54
	v_readlane_b32 s24, v254, 51
	v_readlane_b32 s8, v254, 25
	v_readlane_b32 s9, v254, 26
	v_readlane_b32 s20, v254, 27
	v_readlane_b32 s21, v254, 28
	s_add_u32 s22, s22, 1
	v_mov_b32_e32 v0, s24
	ds_read_b32 v2, v0
	s_add_u32 s8, s8, 0x2c00
	s_addc_u32 s9, s9, 0
	s_add_u32 s20, s20, 0x2c00
	s_addc_u32 s21, s21, 0
	v_writelane_b32 v255, s22, 54
	v_mov_b32_e32 v1, 1
	v_mov_b32_e32 v3, 0
	s_nop 1
	global_atomic_add v4, v3, v1, s[8:9] sc0
	s_waitcnt vmcnt(0) lgkmcnt(0)
	v_readfirstlane_b32 s24, v4
	v_readfirstlane_b32 s23, v2
	buffer_inv sc1
	s_add_u32 s24, s24, 1
	s_mul_i32 s25, s23, s22
	s_cmp_lg_u32 s24, s25
	s_cbranch_scc1 .Lgd_notlast_3
	buffer_wbl2 sc1
	s_waitcnt vmcnt(0)
	v_readlane_b32 s8, v254, 29
	v_readlane_b32 s9, v254, 30
	v_mov_b32_e32 v5, s23
	s_add_u32 s8, s8, 0x1c00
	s_addc_u32 s9, s9, 0
	s_nop 4
	global_atomic_add v3, v5, s[8:9]
	global_atomic_add v3, v5, s[8:9] offset:256
	global_atomic_add v3, v5, s[8:9] offset:512
	global_atomic_add v3, v5, s[8:9] offset:768
	global_atomic_add v3, v5, s[8:9] offset:1024
	global_atomic_add v3, v5, s[8:9] offset:1280
	global_atomic_add v3, v5, s[8:9] offset:1536
	global_atomic_add v3, v5, s[8:9] offset:1792
	global_atomic_add v3, v5, s[8:9] offset:2048
	global_atomic_add v3, v5, s[8:9] offset:2304
	global_atomic_add v3, v5, s[8:9] offset:2560
	global_atomic_add v3, v5, s[8:9] offset:2816
	global_atomic_add v3, v5, s[8:9] offset:3072
	global_atomic_add v3, v5, s[8:9] offset:3328
	global_atomic_add v3, v5, s[8:9] offset:3584
	global_atomic_add v3, v5, s[8:9] offset:3840

; __device__ __forceinline__ unsigned xb_ld(unsigned* p)              { return __hip_atomic_load(p, __ATOMIC_RELAXED, __HIP_MEMORY_SCOPE_AGENT); }
; __device__ __forceinline__ unsigned xb_add(unsigned* p, unsigned v) { return __hip_atomic_fetch_add(p, v, __ATOMIC_RELAXED, __HIP_MEMORY_SCOPE_AGENT); }
; #define XB_SPIN(cond, bar) do { unsigned _sp = 0; while (cond) { __builtin_amdgcn_s_sleep(1); \
;     if ((++_sp & 255u) == 0u) { if (xb_ld(&(bar)[XB_TMO])) break; if (_sp > XB_SPIN_CAP) { atomicAdd(&(bar)[XB_TMO], 1u); break; } } } } while (0)
; __device__ __forceinline__ void xcd_barrier(const XcdBarrier& b) {
;     ...
;         __builtin_amdgcn_s_waitcnt(0);
;         unsigned nloc = b.st[0], nx = b.st[1];
;         if (nloc == 0u) { xcd_barrier_complete(bar, b.x, nloc, nx); b.st[0] = nloc; b.st[1] = nx; }
;         const unsigned old = xb_add(&bar[XB_XSUB(b.x)], 1u);
;         const unsigned gen = old / nloc;
;         if (old + 1u == (gen + 1u) * nloc) {
;             __builtin_amdgcn_fence(__ATOMIC_RELEASE, "agent");
;             asm volatile("s_waitcnt vmcnt(0)" ::: "memory");
;             const unsigned og = xb_add(&bar[XB_TOP], 1u);
;             const unsigned tg = og / nx;
;             __builtin_amdgcn_fence(__ATOMIC_ACQUIRE, "agent");
;             if (og + 1u == (tg + 1u) * nx) xb_add(&bar[XB_TOPGEN], 1u);
;             else XB_SPIN(xb_ld(&bar[XB_TOPGEN]) == tg, bar);
;             xb_add(&bar[XB_XGEN(b.x)], 1u);
.LBB0_1025:
	s_waitcnt vmcnt(0) lgkmcnt(0)
	v_readlane_b32 s22, v255, 54
	v_readlane_b32 s24, v254, 51
	v_readlane_b32 s8, v254, 25
	v_readlane_b32 s9, v254, 26
	v_readlane_b32 s20, v254, 27
	v_readlane_b32 s21, v254, 28
	s_add_u32 s22, s22, 1
	v_mov_b32_e32 v0, s24
	ds_read_b32 v2, v0
	s_add_u32 s8, s8, 0x2c00
	s_addc_u32 s9, s9, 0
	s_add_u32 s20, s20, 0x2c00
	s_addc_u32 s21, s21, 0
	v_writelane_b32 v255, s22, 54
	v_mov_b32_e32 v1, 1
	v_mov_b32_e32 v3, 0
	s_nop 1
	global_atomic_add v4, v3, v1, s[8:9] sc0
	s_waitcnt vmcnt(0) lgkmcnt(0)
	v_readfirstlane_b32 s24, v4
	v_readfirstlane_b32 s23, v2
	buffer_inv sc1
	s_add_u32 s24, s24, 1
	s_mul_i32 s25, s23, s22
	s_cmp_lg_u32 s24, s25
	s_cbranch_scc1 .Lgd_notlast_5
	buffer_wbl2 sc1
	s_waitcnt vmcnt(0)
	v_readlane_b32 s8, v254, 29
	v_readlane_b32 s9, v254, 30
	v_mov_b32_e32 v5, s23
	s_add_u32 s8, s8, 0x1c00
	s_addc_u32 s9, s9, 0
	s_nop 4
	global_atomic_add v3, v5, s[8:9]
	global_atomic_add v3, v5, s[8:9] offset:256
	global_atomic_add v3, v5, s[8:9] offset:512
	global_atomic_add v3, v5, s[8:9] offset:768
	global_atomic_add v3, v5, s[8:9] offset:1024
	global_atomic_add v3, v5, s[8:9] offset:1280
	global_atomic_add v3, v5, s[8:9] offset:1536
	global_atomic_add v3, v5, s[8:9] offset:1792
	global_atomic_add v3, v5, s[8:9] offset:2048
	global_atomic_add v3, v5, s[8:9] offset:2304
	global_atomic_add v3, v5, s[8:9] offset:2560
	global_atomic_add v3, v5, s[8:9] offset:2816
	global_atomic_add v3, v5, s[8:9] offset:3072
	global_atomic_add v3, v5, s[8:9] offset:3328
	global_atomic_add v3, v5, s[8:9] offset:3584
	global_atomic_add v3, v5, s[8:9] offset:3840
